# robust row-scale caching plus one s_nop so that the code after it keeps its previous 8-byte placement (the unpadded build was about 1 percent slower)
# speedup vs baseline: 1.0097x; 1.0097x over previous
.LBB0_189:
	s_add_u32 s1, s68, 0xfff80080
	s_addc_u32 s2, s69, -1
	s_add_i32 s3, 0, 0x10000
	v_add_u32_e32 v154, s3, v143
	ds_read_b128 v[138:141], v154
	ds_read_b128 v[146:149], v154 offset:1024
	ds_read_b128 v[150:153], v154 offset:2048
	ds_read_b128 v[154:157], v154 offset:3072
	s_cmp_eq_u32 s87, 28
	s_cselect_b32 s73, s43, s2
	s_cselect_b32 s72, s81, s1
	s_cselect_b32 s71, s41, s86
	s_cselect_b32 s70, s82, s83
	v_lshl_add_u64 v[174:175], s[68:69], 0, v[134:135]
	s_add_i32 m0, s60, 0xc000
	ds_read_b128 v[158:161], v145
	ds_read_b128 v[162:165], v145 offset:1024
	ds_read_b128 v[166:169], v145 offset:2048
	ds_read_b128 v[170:173], v145 offset:3072
	ds_read_b128 v[182:185], v145 offset:4096
	ds_read_b128 v[206:209], v145 offset:5120
	ds_read_b128 v[210:213], v145 offset:6144
	ds_read_b128 v[214:217], v145 offset:7168
	global_load_lds_dwordx4 v[174:175], off
	v_lshl_add_u64 v[174:175], s[68:69], 0, v[136:137]
	s_add_i32 m0, s60, 0xe000
	s_nop 0
	global_load_lds_dwordx4 v[174:175], off
	s_waitcnt lgkmcnt(8)
	s_barrier
	s_waitcnt lgkmcnt(0)
	s_setprio 1
	s_waitcnt lgkmcnt(0)
	v_mfma_f32_16x16x32_bf16 v[124:127], v[138:141], v[158:161], v[124:127]
	v_mfma_f32_16x16x32_bf16 v[120:123], v[150:153], v[158:161], v[120:123]
	v_mfma_f32_16x16x32_bf16 v[116:119], v[138:141], v[166:169], v[116:119]
	v_mfma_f32_16x16x32_bf16 v[108:111], v[150:153], v[166:169], v[108:111]
	v_mfma_f32_16x16x32_bf16 v[100:103], v[138:141], v[182:185], v[100:103]
	v_mfma_f32_16x16x32_bf16 v[92:95], v[150:153], v[182:185], v[92:95]
	v_mfma_f32_16x16x32_bf16 v[84:87], v[138:141], v[210:213], v[84:87]
	v_mfma_f32_16x16x32_bf16 v[76:79], v[150:153], v[210:213], v[76:79]
	v_mfma_f32_16x16x32_bf16 v[124:127], v[146:149], v[162:165], v[124:127]
	v_mfma_f32_16x16x32_bf16 v[120:123], v[154:157], v[162:165], v[120:123]
	v_mfma_f32_16x16x32_bf16 v[116:119], v[146:149], v[170:173], v[116:119]
	v_mfma_f32_16x16x32_bf16 v[108:111], v[154:157], v[170:173], v[108:111]
	v_mfma_f32_16x16x32_bf16 v[100:103], v[146:149], v[206:209], v[100:103]
	v_mfma_f32_16x16x32_bf16 v[92:95], v[154:157], v[206:209], v[92:95]
	v_mfma_f32_16x16x32_bf16 v[84:87], v[146:149], v[214:217], v[84:87]
	v_mfma_f32_16x16x32_bf16 v[76:79], v[154:157], v[214:217], v[76:79]
	s_setprio 0
	s_barrier
	s_add_i32 s1, 0, 0x14000
	v_add_u32_e32 v174, s1, v143
	s_add_i32 s2, s3, s53
	ds_read_b128 v[218:221], v174
	ds_read_b128 v[222:225], v174 offset:1024
	ds_read_b128 v[226:229], v174 offset:2048
	ds_read_b128 v[230:233], v174 offset:3072
	v_lshl_add_u64 v[174:175], s[70:71], 0, v[176:177]
	s_mov_b32 m0, s2
	v_lshl_add_u64 v[186:187], s[70:71], 0, v[128:129]
	global_load_lds_dwordx4 v[174:175], off
	s_add_i32 m0, s2, 0x2000
	s_nop 0
	global_load_lds_dwordx4 v[186:187], off
	s_barrier
	s_waitcnt lgkmcnt(0)
	s_setprio 1
	s_waitcnt lgkmcnt(0)
	v_mfma_f32_16x16x32_bf16 v[112:115], v[218:221], v[158:161], v[112:115]
	v_mfma_f32_16x16x32_bf16 v[104:107], v[226:229], v[158:161], v[104:107]
	v_mfma_f32_16x16x32_bf16 v[96:99], v[218:221], v[166:169], v[96:99]
	v_mfma_f32_16x16x32_bf16 v[88:91], v[226:229], v[166:169], v[88:91]
	v_mfma_f32_16x16x32_bf16 v[80:83], v[218:221], v[182:185], v[80:83]
	v_mfma_f32_16x16x32_bf16 v[72:75], v[226:229], v[182:185], v[72:75]
	v_mfma_f32_16x16x32_bf16 v[68:71], v[218:221], v[210:213], v[68:71]
	v_mfma_f32_16x16x32_bf16 v[64:67], v[226:229], v[210:213], v[64:67]
	v_mfma_f32_16x16x32_bf16 v[112:115], v[222:225], v[162:165], v[112:115]
	v_mfma_f32_16x16x32_bf16 v[104:107], v[230:233], v[162:165], v[104:107]
	v_mfma_f32_16x16x32_bf16 v[96:99], v[222:225], v[170:173], v[96:99]
	v_mfma_f32_16x16x32_bf16 v[88:91], v[230:233], v[170:173], v[88:91]
	v_mfma_f32_16x16x32_bf16 v[80:83], v[222:225], v[206:209], v[80:83]
	v_mfma_f32_16x16x32_bf16 v[72:75], v[230:233], v[206:209], v[72:75]
	v_mfma_f32_16x16x32_bf16 v[68:71], v[222:225], v[214:217], v[68:71]
	v_mfma_f32_16x16x32_bf16 v[64:67], v[230:233], v[214:217], v[64:67]
	s_setprio 0
	s_mov_b32 m0, s60
	v_lshl_add_u64 v[200:201], s[72:73], 0, v[132:133]
	s_barrier
	ds_read_b128 v[158:161], v145 offset:16384
	ds_read_b128 v[162:165], v145 offset:17408
	ds_read_b128 v[166:169], v145 offset:18432
	ds_read_b128 v[170:173], v145 offset:19456
	ds_read_b128 v[182:185], v145 offset:20480
	ds_read_b128 v[206:209], v145 offset:21504
	ds_read_b128 v[210:213], v145 offset:22528
	ds_read_b128 v[214:217], v145 offset:23552
	global_load_lds_dwordx4 v[200:201], off
	v_lshl_add_u64 v[202:203], s[72:73], 0, v[130:131]
	s_mov_b32 m0, s61
	s_nop 0
	global_load_lds_dwordx4 v[202:203], off
	s_barrier
	s_waitcnt lgkmcnt(0)
	s_setprio 1
	s_waitcnt lgkmcnt(0)
	v_mfma_f32_16x16x32_bf16 v[60:63], v[138:141], v[158:161], v[60:63]
	v_mfma_f32_16x16x32_bf16 v[56:59], v[150:153], v[158:161], v[56:59]
	v_mfma_f32_16x16x32_bf16 v[52:55], v[138:141], v[166:169], v[52:55]
	v_mfma_f32_16x16x32_bf16 v[44:47], v[150:153], v[166:169], v[44:47]
	v_mfma_f32_16x16x32_bf16 v[36:39], v[138:141], v[182:185], v[36:39]
	v_mfma_f32_16x16x32_bf16 v[28:31], v[150:153], v[182:185], v[28:31]
	v_mfma_f32_16x16x32_bf16 v[20:23], v[138:141], v[210:213], v[20:23]
	v_mfma_f32_16x16x32_bf16 v[12:15], v[150:153], v[210:213], v[12:15]
	v_mfma_f32_16x16x32_bf16 v[60:63], v[146:149], v[162:165], v[60:63]
	v_mfma_f32_16x16x32_bf16 v[56:59], v[154:157], v[162:165], v[56:59]
	v_mfma_f32_16x16x32_bf16 v[52:55], v[146:149], v[170:173], v[52:55]
	v_mfma_f32_16x16x32_bf16 v[44:47], v[154:157], v[170:173], v[44:47]
	v_mfma_f32_16x16x32_bf16 v[36:39], v[146:149], v[206:209], v[36:39]
	v_mfma_f32_16x16x32_bf16 v[28:31], v[154:157], v[206:209], v[28:31]
	v_mfma_f32_16x16x32_bf16 v[20:23], v[146:149], v[214:217], v[20:23]
	v_mfma_f32_16x16x32_bf16 v[12:15], v[154:157], v[214:217], v[12:15]
	s_setprio 0
	s_barrier
	s_add_u32 s2, s70, 0x80000
	s_addc_u32 s3, s71, 0
	s_add_i32 s1, s1, s53
	v_lshl_add_u64 v[138:139], s[2:3], 0, v[176:177]
	s_mov_b32 m0, s1
	s_nop 0
	global_load_lds_dwordx4 v[138:139], off
	v_lshl_add_u64 v[138:139], s[2:3], 0, v[128:129]
	s_add_i32 m0, s1, 0x2000
	s_nop 0
	global_load_lds_dwordx4 v[138:139], off
	s_waitcnt vmcnt(6)
	s_barrier
	s_setprio 1
	v_mfma_f32_16x16x32_bf16 v[48:51], v[218:221], v[158:161], v[48:51]
	v_mfma_f32_16x16x32_bf16 v[40:43], v[226:229], v[158:161], v[40:43]
	v_mfma_f32_16x16x32_bf16 v[32:35], v[218:221], v[166:169], v[32:35]
	v_mfma_f32_16x16x32_bf16 v[24:27], v[226:229], v[166:169], v[24:27]
	v_mfma_f32_16x16x32_bf16 v[16:19], v[218:221], v[182:185], v[16:19]
	v_mfma_f32_16x16x32_bf16 v[8:11], v[226:229], v[182:185], v[8:11]
	v_mfma_f32_16x16x32_bf16 v[4:7], v[218:221], v[210:213], v[4:7]
	v_mfma_f32_16x16x32_bf16 v[0:3], v[226:229], v[210:213], v[0:3]
	v_mfma_f32_16x16x32_bf16 v[48:51], v[222:225], v[162:165], v[48:51]
	v_mfma_f32_16x16x32_bf16 v[40:43], v[230:233], v[162:165], v[40:43]
	v_mfma_f32_16x16x32_bf16 v[32:35], v[222:225], v[170:173], v[32:35]
	v_mfma_f32_16x16x32_bf16 v[24:27], v[230:233], v[170:173], v[24:27]
	v_mfma_f32_16x16x32_bf16 v[16:19], v[222:225], v[206:209], v[16:19]
	v_mfma_f32_16x16x32_bf16 v[8:11], v[230:233], v[206:209], v[8:11]
	v_mfma_f32_16x16x32_bf16 v[4:7], v[222:225], v[214:217], v[4:7]
	v_mfma_f32_16x16x32_bf16 v[0:3], v[230:233], v[214:217], v[0:3]
	s_setprio 0
	s_add_i32 s1, 0, 0x18000
	v_add_u32_e32 v154, s1, v143
	s_barrier
	ds_read_b128 v[138:141], v154
	ds_read_b128 v[146:149], v154 offset:1024
	ds_read_b128 v[150:153], v154 offset:2048
	ds_read_b128 v[154:157], v154 offset:3072
	s_add_u32 s2, s72, 0x80000
	s_addc_u32 s3, s73, 0
	s_mov_b32 m0, s74
	v_lshl_add_u64 v[204:205], s[2:3], 0, v[132:133]
	ds_read_b128 v[158:161], v145 offset:32768
	ds_read_b128 v[162:165], v145 offset:33792
	ds_read_b128 v[166:169], v145 offset:34816
	ds_read_b128 v[170:173], v145 offset:35840
	ds_read_b128 v[182:185], v145 offset:36864
	ds_read_b128 v[206:209], v145 offset:37888
	ds_read_b128 v[210:213], v145 offset:38912
	ds_read_b128 v[214:217], v145 offset:39936
	global_load_lds_dwordx4 v[204:205], off
	v_lshl_add_u64 v[204:205], s[2:3], 0, v[130:131]
	s_mov_b32 m0, s75
	s_nop 0
	global_load_lds_dwordx4 v[204:205], off
	s_waitcnt lgkmcnt(8)
	s_barrier
	s_waitcnt lgkmcnt(0)
	s_setprio 1
	s_waitcnt lgkmcnt(0)
	v_mfma_f32_16x16x32_bf16 v[124:127], v[138:141], v[158:161], v[124:127]
	v_mfma_f32_16x16x32_bf16 v[120:123], v[150:153], v[158:161], v[120:123]
	v_mfma_f32_16x16x32_bf16 v[116:119], v[138:141], v[166:169], v[116:119]
	v_mfma_f32_16x16x32_bf16 v[108:111], v[150:153], v[166:169], v[108:111]
	v_mfma_f32_16x16x32_bf16 v[100:103], v[138:141], v[182:185], v[100:103]
	v_mfma_f32_16x16x32_bf16 v[92:95], v[150:153], v[182:185], v[92:95]
	v_mfma_f32_16x16x32_bf16 v[84:87], v[138:141], v[210:213], v[84:87]
	v_mfma_f32_16x16x32_bf16 v[76:79], v[150:153], v[210:213], v[76:79]
	v_mfma_f32_16x16x32_bf16 v[124:127], v[146:149], v[162:165], v[124:127]
	v_mfma_f32_16x16x32_bf16 v[120:123], v[154:157], v[162:165], v[120:123]
	v_mfma_f32_16x16x32_bf16 v[116:119], v[146:149], v[170:173], v[116:119]
	v_mfma_f32_16x16x32_bf16 v[108:111], v[154:157], v[170:173], v[108:111]
	v_mfma_f32_16x16x32_bf16 v[100:103], v[146:149], v[206:209], v[100:103]
	v_mfma_f32_16x16x32_bf16 v[92:95], v[154:157], v[206:209], v[92:95]
	v_mfma_f32_16x16x32_bf16 v[84:87], v[146:149], v[214:217], v[84:87]
	v_mfma_f32_16x16x32_bf16 v[76:79], v[154:157], v[214:217], v[76:79]
	s_setprio 0
	s_barrier
	s_add_i32 s12, 0, 0x1c000
	s_add_i32 s1, s1, s53
	v_add_u32_e32 v188, s12, v143
	v_lshl_add_u64 v[174:175], v[174:175], 0, s[20:21]
	s_mov_b32 m0, s1
	ds_read_b128 v[218:221], v188
	ds_read_b128 v[222:225], v188 offset:1024
	ds_read_b128 v[226:229], v188 offset:2048
	ds_read_b128 v[230:233], v188 offset:3072
	global_load_lds_dwordx4 v[174:175], off
	v_lshl_add_u64 v[174:175], v[186:187], 0, s[20:21]
	s_add_i32 m0, s1, 0x2000
	s_nop 0
	global_load_lds_dwordx4 v[174:175], off
	s_barrier
	s_waitcnt lgkmcnt(0)
	s_setprio 1
	s_waitcnt lgkmcnt(0)
	v_mfma_f32_16x16x32_bf16 v[112:115], v[218:221], v[158:161], v[112:115]
	v_mfma_f32_16x16x32_bf16 v[104:107], v[226:229], v[158:161], v[104:107]
	v_mfma_f32_16x16x32_bf16 v[96:99], v[218:221], v[166:169], v[96:99]
	v_mfma_f32_16x16x32_bf16 v[88:91], v[226:229], v[166:169], v[88:91]
	v_mfma_f32_16x16x32_bf16 v[80:83], v[218:221], v[182:185], v[80:83]
	v_mfma_f32_16x16x32_bf16 v[72:75], v[226:229], v[182:185], v[72:75]
	v_mfma_f32_16x16x32_bf16 v[68:71], v[218:221], v[210:213], v[68:71]
	v_mfma_f32_16x16x32_bf16 v[64:67], v[226:229], v[210:213], v[64:67]
	v_mfma_f32_16x16x32_bf16 v[112:115], v[222:225], v[162:165], v[112:115]
	v_mfma_f32_16x16x32_bf16 v[104:107], v[230:233], v[162:165], v[104:107]
	v_mfma_f32_16x16x32_bf16 v[96:99], v[222:225], v[170:173], v[96:99]
	v_mfma_f32_16x16x32_bf16 v[88:91], v[230:233], v[170:173], v[88:91]
	v_mfma_f32_16x16x32_bf16 v[80:83], v[222:225], v[206:209], v[80:83]
	v_mfma_f32_16x16x32_bf16 v[72:75], v[230:233], v[206:209], v[72:75]
	v_mfma_f32_16x16x32_bf16 v[68:71], v[222:225], v[214:217], v[68:71]
	v_mfma_f32_16x16x32_bf16 v[64:67], v[230:233], v[214:217], v[64:67]
	s_setprio 0
	s_mov_b32 m0, s76
	v_lshl_add_u64 v[174:175], v[200:201], 0, s[20:21]
	s_barrier
	ds_read_b128 v[158:161], v145 offset:49152
	ds_read_b128 v[162:165], v145 offset:50176
	ds_read_b128 v[166:169], v145 offset:51200
	ds_read_b128 v[170:173], v145 offset:52224
	ds_read_b128 v[182:185], v145 offset:53248
	ds_read_b128 v[206:209], v145 offset:54272
	ds_read_b128 v[210:213], v145 offset:55296
	ds_read_b128 v[214:217], v145 offset:56320
	global_load_lds_dwordx4 v[174:175], off
	v_lshl_add_u64 v[174:175], v[202:203], 0, s[20:21]
	s_mov_b32 m0, s77
	s_nop 0
	global_load_lds_dwordx4 v[174:175], off
	s_barrier
	s_waitcnt lgkmcnt(0)
	s_setprio 1
	s_waitcnt lgkmcnt(0)
	v_mfma_f32_16x16x32_bf16 v[60:63], v[138:141], v[158:161], v[60:63]
	v_mfma_f32_16x16x32_bf16 v[56:59], v[150:153], v[158:161], v[56:59]
	v_mfma_f32_16x16x32_bf16 v[52:55], v[138:141], v[166:169], v[52:55]
	v_mfma_f32_16x16x32_bf16 v[44:47], v[150:153], v[166:169], v[44:47]
	v_mfma_f32_16x16x32_bf16 v[36:39], v[138:141], v[182:185], v[36:39]
	v_mfma_f32_16x16x32_bf16 v[28:31], v[150:153], v[182:185], v[28:31]
	v_mfma_f32_16x16x32_bf16 v[20:23], v[138:141], v[210:213], v[20:23]
	v_mfma_f32_16x16x32_bf16 v[12:15], v[150:153], v[210:213], v[12:15]
	v_mfma_f32_16x16x32_bf16 v[60:63], v[146:149], v[162:165], v[60:63]
	v_mfma_f32_16x16x32_bf16 v[56:59], v[154:157], v[162:165], v[56:59]
	v_mfma_f32_16x16x32_bf16 v[52:55], v[146:149], v[170:173], v[52:55]
	v_mfma_f32_16x16x32_bf16 v[44:47], v[154:157], v[170:173], v[44:47]
	v_mfma_f32_16x16x32_bf16 v[36:39], v[146:149], v[206:209], v[36:39]
	v_mfma_f32_16x16x32_bf16 v[28:31], v[154:157], v[206:209], v[28:31]
	v_mfma_f32_16x16x32_bf16 v[20:23], v[146:149], v[214:217], v[20:23]
	v_mfma_f32_16x16x32_bf16 v[12:15], v[154:157], v[214:217], v[12:15]
	s_setprio 0
	s_barrier
	s_add_u32 s2, s70, 0x80080
	s_addc_u32 s3, s71, 0
	s_add_i32 s1, s12, s53
	v_lshl_add_u64 v[138:139], s[2:3], 0, v[176:177]
	s_mov_b32 m0, s1
	s_nop 0
	global_load_lds_dwordx4 v[138:139], off
	v_lshl_add_u64 v[138:139], s[2:3], 0, v[128:129]
	s_add_i32 m0, s1, 0x2000
	s_nop 0
	global_load_lds_dwordx4 v[138:139], off
	s_waitcnt vmcnt(6)
	s_barrier
	s_setprio 1
	v_mfma_f32_16x16x32_bf16 v[48:51], v[218:221], v[158:161], v[48:51]
	v_mfma_f32_16x16x32_bf16 v[40:43], v[226:229], v[158:161], v[40:43]
	v_mfma_f32_16x16x32_bf16 v[32:35], v[218:221], v[166:169], v[32:35]
	v_mfma_f32_16x16x32_bf16 v[24:27], v[226:229], v[166:169], v[24:27]
	v_mfma_f32_16x16x32_bf16 v[16:19], v[218:221], v[182:185], v[16:19]
	v_mfma_f32_16x16x32_bf16 v[8:11], v[226:229], v[182:185], v[8:11]
	v_mfma_f32_16x16x32_bf16 v[4:7], v[218:221], v[210:213], v[4:7]
	v_mfma_f32_16x16x32_bf16 v[0:3], v[226:229], v[210:213], v[0:3]
	v_mfma_f32_16x16x32_bf16 v[48:51], v[222:225], v[162:165], v[48:51]
	v_mfma_f32_16x16x32_bf16 v[40:43], v[230:233], v[162:165], v[40:43]
	v_mfma_f32_16x16x32_bf16 v[32:35], v[222:225], v[170:173], v[32:35]
	v_mfma_f32_16x16x32_bf16 v[24:27], v[230:233], v[170:173], v[24:27]
	v_mfma_f32_16x16x32_bf16 v[16:19], v[222:225], v[206:209], v[16:19]
	v_mfma_f32_16x16x32_bf16 v[8:11], v[230:233], v[206:209], v[8:11]
	v_mfma_f32_16x16x32_bf16 v[4:7], v[222:225], v[214:217], v[4:7]
	v_mfma_f32_16x16x32_bf16 v[0:3], v[230:233], v[214:217], v[0:3]
	s_setprio 0
	s_add_i32 s87, s87, 2
	s_add_u32 s68, s68, 0x100
	s_addc_u32 s69, s69, 0
	s_add_u32 s83, s83, 0x100
	s_addc_u32 s86, s86, 0
	s_cmp_gt_u32 s87, 29
	s_barrier
	s_cbranch_scc0 .LBB0_189
	s_cmp_eq_u32 s88, 0
	s_cbranch_scc1 .Lrs_skip
	s_add_i32 s98, s80, 1
	s_nop 0
	s_cmp_eq_u32 s89, s98
	s_cbranch_scc1 .Lrs_mul
	v_readlane_b32 s98, v255, 1
	v_readlane_b32 s99, v255, 2
	v_lshl_add_u32 v200, s80, 8, v142
	v_bfe_u32 v201, v144, 3, 2
	v_lshlrev_b32_e32 v201, 5, v201
	v_lshl_add_u32 v200, v200, 7, v201
	v_add_u32_e32 v201, 0x1000, v200
	v_add_u32_e32 v202, 0x4000, v200
	v_add_u32_e32 v203, 0x5000, v200
	v_mbcnt_lo_u32_b32 v204, -1, 0
	v_mbcnt_hi_u32_b32 v204, -1, v204
	v_xor_b32_e32 v205, 16, v204
	v_xor_b32_e32 v204, 32, v204
	v_lshlrev_b32_e32 v205, 2, v205
	v_lshlrev_b32_e32 v204, 2, v204
	global_load_dwordx4 v[208:211], v200, s[98:99]
	global_load_dwordx4 v[212:215], v200, s[98:99] offset:16
	global_load_dwordx4 v[216:219], v200, s[98:99] offset:2048
	global_load_dwordx4 v[220:223], v200, s[98:99] offset:2064
	global_load_dwordx4 v[224:227], v201, s[98:99]
	global_load_dwordx4 v[228:231], v201, s[98:99] offset:16
	global_load_dwordx4 v[232:235], v201, s[98:99] offset:2048
	global_load_dwordx4 v[236:239], v201, s[98:99] offset:2064
	s_waitcnt vmcnt(0)
	v_add_f32_e32 v208, v208, v209
	v_add_f32_e32 v210, v210, v211
	v_add_f32_e32 v212, v212, v213
	v_add_f32_e32 v214, v214, v215
	v_add_f32_e32 v208, v208, v210
	v_add_f32_e32 v212, v212, v214
	v_add_f32_e32 v190, v208, v212
	v_add_f32_e32 v216, v216, v217
	v_add_f32_e32 v218, v218, v219
	v_add_f32_e32 v220, v220, v221
	v_add_f32_e32 v222, v222, v223
	v_add_f32_e32 v216, v216, v218
	v_add_f32_e32 v220, v220, v222
	v_add_f32_e32 v191, v216, v220
	v_add_f32_e32 v224, v224, v225
	v_add_f32_e32 v226, v226, v227
	v_add_f32_e32 v228, v228, v229
	v_add_f32_e32 v230, v230, v231
	v_add_f32_e32 v224, v224, v226
	v_add_f32_e32 v228, v228, v230
	v_add_f32_e32 v192, v224, v228
	v_add_f32_e32 v232, v232, v233
	v_add_f32_e32 v234, v234, v235
	v_add_f32_e32 v236, v236, v237
	v_add_f32_e32 v238, v238, v239
	v_add_f32_e32 v232, v232, v234
	v_add_f32_e32 v236, v236, v238
	v_add_f32_e32 v194, v232, v236
	global_load_dwordx4 v[208:211], v202, s[98:99]
	global_load_dwordx4 v[212:215], v202, s[98:99] offset:16
	global_load_dwordx4 v[216:219], v202, s[98:99] offset:2048
	global_load_dwordx4 v[220:223], v202, s[98:99] offset:2064
	global_load_dwordx4 v[224:227], v203, s[98:99]
	global_load_dwordx4 v[228:231], v203, s[98:99] offset:16
	global_load_dwordx4 v[232:235], v203, s[98:99] offset:2048
	global_load_dwordx4 v[236:239], v203, s[98:99] offset:2064
	s_waitcnt vmcnt(0)
	v_add_f32_e32 v208, v208, v209
	v_add_f32_e32 v210, v210, v211
	v_add_f32_e32 v212, v212, v213
	v_add_f32_e32 v214, v214, v215
	v_add_f32_e32 v208, v208, v210
	v_add_f32_e32 v212, v212, v214
	v_add_f32_e32 v195, v208, v212
	v_add_f32_e32 v216, v216, v217
	v_add_f32_e32 v218, v218, v219
	v_add_f32_e32 v220, v220, v221
	v_add_f32_e32 v222, v222, v223
	v_add_f32_e32 v216, v216, v218
	v_add_f32_e32 v220, v220, v222
	v_add_f32_e32 v196, v216, v220
	v_add_f32_e32 v224, v224, v225
	v_add_f32_e32 v226, v226, v227
	v_add_f32_e32 v228, v228, v229
	v_add_f32_e32 v230, v230, v231
	v_add_f32_e32 v224, v224, v226
	v_add_f32_e32 v228, v228, v230
	v_add_f32_e32 v198, v224, v228
	v_add_f32_e32 v232, v232, v233
	v_add_f32_e32 v234, v234, v235
	v_add_f32_e32 v236, v236, v237
	v_add_f32_e32 v238, v238, v239
	v_add_f32_e32 v232, v232, v234
	v_add_f32_e32 v236, v236, v238
	v_add_f32_e32 v248, v232, v236
	ds_bpermute_b32 v240, v205, v190
	ds_bpermute_b32 v241, v205, v191
	ds_bpermute_b32 v242, v205, v192
	ds_bpermute_b32 v243, v205, v194
	ds_bpermute_b32 v244, v205, v195
	ds_bpermute_b32 v245, v205, v196
	ds_bpermute_b32 v246, v205, v198
	ds_bpermute_b32 v247, v205, v248
	s_waitcnt lgkmcnt(0)
	v_add_f32_e32 v190, v190, v240
	v_add_f32_e32 v191, v191, v241
	v_add_f32_e32 v192, v192, v242
	v_add_f32_e32 v194, v194, v243
	v_add_f32_e32 v195, v195, v244
	v_add_f32_e32 v196, v196, v245
	v_add_f32_e32 v198, v198, v246
	v_add_f32_e32 v248, v248, v247
	ds_bpermute_b32 v240, v204, v190
	ds_bpermute_b32 v241, v204, v191
	ds_bpermute_b32 v242, v204, v192
	ds_bpermute_b32 v243, v204, v194
	ds_bpermute_b32 v244, v204, v195
	ds_bpermute_b32 v245, v204, v196
	ds_bpermute_b32 v246, v204, v198
	ds_bpermute_b32 v247, v204, v248
	s_waitcnt lgkmcnt(0)
	v_add_f32_e32 v190, v190, v240
	v_add_f32_e32 v191, v191, v241
	v_add_f32_e32 v192, v192, v242
	v_add_f32_e32 v194, v194, v243
	v_add_f32_e32 v195, v195, v244
	v_add_f32_e32 v196, v196, v245
	v_add_f32_e32 v198, v198, v246
	v_add_f32_e32 v248, v248, v247
	v_mul_f32_e32 v190, 0x3a000000, v190
	v_add_f32_e32 v190, 0x358637bd, v190
	v_mul_f32_e32 v191, 0x3a000000, v191
	v_add_f32_e32 v191, 0x358637bd, v191
	v_mul_f32_e32 v192, 0x3a000000, v192
	v_add_f32_e32 v192, 0x358637bd, v192
	v_mul_f32_e32 v194, 0x3a000000, v194
	v_add_f32_e32 v194, 0x358637bd, v194
	v_mul_f32_e32 v195, 0x3a000000, v195
	v_add_f32_e32 v195, 0x358637bd, v195
	v_mul_f32_e32 v196, 0x3a000000, v196
	v_add_f32_e32 v196, 0x358637bd, v196
	v_mul_f32_e32 v198, 0x3a000000, v198
	v_add_f32_e32 v198, 0x358637bd, v198
	v_mul_f32_e32 v248, 0x3a000000, v248
	v_add_f32_e32 v248, 0x358637bd, v248
	v_rsq_f32_e32 v190, v190
	v_rsq_f32_e32 v191, v191
	v_rsq_f32_e32 v192, v192
	v_rsq_f32_e32 v194, v194
	v_rsq_f32_e32 v195, v195
	v_rsq_f32_e32 v196, v196
	v_rsq_f32_e32 v198, v198
	v_rsq_f32_e32 v248, v248
	s_add_i32 s89, s80, 1
